# diff attention second-map epilogue: sub-LN cross-lane reductions of the 16 rows overlapped (stage-wise emission), same arithmetic
# speedup vs baseline: 1.0003x; 1.0000x over previous
; #define SBAR() __builtin_amdgcn_sched_barrier(0)
; template <int OFF> __device__ __forceinline__ s16x4 tr_read(int vb) { s16x4 r; asm volatile("ds_read_b64_tr_b16 %0, %1 offset:%2" : "=&v"(r) : "v"(vb), "i"(OFF) : "memory"); return r; }
; template <int D0> __device__ __forceinline__ void pv_one(f32x16& od, int vb, bf16x8 pa0, bf16x8 pa1, bf16x8 pa2, bf16x8 pa3) {
;     const s16x4 l0 = tr_read<v_rd_off(D0, 0, 0)>(vb), h0 = tr_read<v_rd_off(D0, 0, 1)>(vb), l1 = tr_read<v_rd_off(D0, 1, 0)>(vb), h1 = tr_read<v_rd_off(D0, 1, 1)>(vb);
;     const s16x4 l2 = tr_read<v_rd_off(D0, 2, 0)>(vb), h2 = tr_read<v_rd_off(D0, 2, 1)>(vb), l3 = tr_read<v_rd_off(D0, 3, 0)>(vb), h3 = tr_read<v_rd_off(D0, 3, 1)>(vb);
;     asm volatile("s_waitcnt lgkmcnt(0)" ::: "memory"); SBAR();
;     ...
;     od = __builtin_amdgcn_mfma_f32_32x32x16_bf16(pa0, PK(l0, h0), od, 0, 0, 0);
;     od = __builtin_amdgcn_mfma_f32_32x32x16_bf16(pa1, PK(l1, h1), od, 0, 0, 0);
;     od = __builtin_amdgcn_mfma_f32_32x32x16_bf16(pa2, PK(l2, h2), od, 0, 0, 0);
;     od = __builtin_amdgcn_mfma_f32_32x32x16_bf16(pa3, PK(l3, h3), od, 0, 0, 0);
;     ...
; }
; __device__ __forceinline__ void pv_d0(f32x16* o, int vb, bf16x8 pa0, bf16x8 pa1, bf16x8 pa2, bf16x8 pa3) {
;     pv_one<0>(o[0], vb, pa0, pa1, pa2, pa3); pv_one<1>(o[1], vb, pa0, pa1, pa2, pa3); pv_one<2>(o[2], vb, pa0, pa1, pa2, pa3); pv_one<3>(o[3], vb, pa0, pa1, pa2, pa3);
; __device__ __forceinline__ void finishSM(f32x16& p0, f32x16& p1, float alpha, float& l_reg, bf16x8& pa0, bf16x8& pa1, bf16x8& pa2, bf16x8& pa3) {
; #pragma unroll
;     for (int r = 0; r < 16; ++r) p1[r] = __builtin_amdgcn_exp2f(p1[r]);
;     float ps = 0;
; #pragma unroll
;     for (int r = 0; r < 16; ++r) ps += p0[r];
; #pragma unroll
;     for (int r = 0; r < 16; ++r) ps += p1[r];
;     { auto rr = __builtin_amdgcn_permlane32_swap(__float_as_uint(ps), __float_as_uint(ps), false, false);
;       ps = __uint_as_float(rr[0]) + __uint_as_float(rr[1]); }
;     l_reg = l_reg * alpha + ps;
;     ...
;     PK4(p0, 0, pa0); PK4(p0, 8, pa1); PK4(p1, 0, pa2); PK4(p1, 8, pa3);
;     ...
; }
; template <int DQK, int DK1, int LDQ, int LDK, int LDKR, int LDV, int NQL, int SDEPTH>
; __device__ __forceinline__ void attn_core(const AttnArgs& a, char* lds, f32x16 (&o)[4]) {
;     ...
;     finishSM(pB0, pB1, alB, l_reg, pa0, pa1, pa2, pa3); SBAR();
;     pv_d0(o, vb0 + SHM_V, pa0, pa1, pa2, pa3);
.LBB0_187:
	v_cndmask_b32_e64 v101, v101, v142, s[14:15]
	v_mul_f32_e32 v101, 0xbe38aa3b, v101
	v_fmamk_f32 v80, v80, 0x3e38aa3b, v101
	v_fmamk_f32 v81, v81, 0x3e38aa3b, v101
	v_fmamk_f32 v102, v82, 0x3e38aa3b, v101
	v_exp_f32_e32 v82, v80
	v_fmamk_f32 v103, v84, 0x3e38aa3b, v101
	v_exp_f32_e32 v84, v81
	v_fmamk_f32 v83, v83, 0x3e38aa3b, v101
	v_exp_f32_e32 v80, v102
	v_fmamk_f32 v64, v64, 0x3e38aa3b, v101
	v_exp_f32_e32 v83, v83
	v_fmamk_f32 v104, v85, 0x3e38aa3b, v101
	v_fmamk_f32 v113, v94, 0x3e38aa3b, v101
	v_fmamk_f32 v94, v75, 0x3e38aa3b, v101
	v_exp_f32_e32 v75, v103
	v_exp_f32_e32 v102, v64
	v_add_f32_e32 v64, 0, v82
	v_fmamk_f32 v105, v86, 0x3e38aa3b, v101
	v_exp_f32_e32 v81, v104
	v_add_f32_e32 v64, v84, v64
	v_fmamk_f32 v106, v87, 0x3e38aa3b, v101
	v_fmamk_f32 v112, v93, 0x3e38aa3b, v101
	v_fmamk_f32 v93, v74, 0x3e38aa3b, v101
	v_exp_f32_e32 v74, v105
	v_add_f32_e32 v64, v80, v64
	v_fmamk_f32 v107, v88, 0x3e38aa3b, v101
	v_fmamk_f32 v114, v95, 0x3e38aa3b, v101
	v_fmamk_f32 v95, v76, 0x3e38aa3b, v101
	v_exp_f32_e32 v76, v106
	v_add_f32_e32 v64, v83, v64
	v_fmamk_f32 v108, v89, 0x3e38aa3b, v101
	v_fmamk_f32 v109, v90, 0x3e38aa3b, v101
	v_fmamk_f32 v90, v71, 0x3e38aa3b, v101
	v_exp_f32_e32 v71, v107
	v_add_f32_e32 v64, v75, v64
	v_fmamk_f32 v111, v92, 0x3e38aa3b, v101
	v_fmamk_f32 v92, v73, 0x3e38aa3b, v101
	v_exp_f32_e32 v73, v108
	v_add_f32_e32 v64, v81, v64
	v_fmamk_f32 v110, v91, 0x3e38aa3b, v101
	v_fmamk_f32 v88, v69, 0x3e38aa3b, v101
	v_exp_f32_e32 v69, v109
	v_add_f32_e32 v64, v74, v64
	v_fmamk_f32 v91, v72, 0x3e38aa3b, v101
	v_exp_f32_e32 v72, v110
	v_add_f32_e32 v64, v76, v64
	v_fmamk_f32 v86, v67, 0x3e38aa3b, v101
	v_exp_f32_e32 v67, v111
	v_add_f32_e32 v64, v71, v64
	v_fmamk_f32 v89, v70, 0x3e38aa3b, v101
	v_exp_f32_e32 v70, v112
	v_add_f32_e32 v64, v73, v64
	v_fmamk_f32 v85, v66, 0x3e38aa3b, v101
	v_exp_f32_e32 v66, v113
	v_add_f32_e32 v64, v69, v64
	v_fmamk_f32 v87, v68, 0x3e38aa3b, v101
	v_exp_f32_e32 v68, v114
	v_add_f32_e32 v64, v72, v64
	v_fmamk_f32 v65, v65, 0x3e38aa3b, v101
	v_add_f32_e32 v64, v67, v64
	v_exp_f32_e32 v103, v65
	v_add_f32_e32 v64, v70, v64
	v_exp_f32_e32 v85, v85
	v_add_f32_e32 v64, v66, v64
	v_exp_f32_e32 v86, v86
	v_add_f32_e32 v64, v68, v64
	v_exp_f32_e32 v87, v87
	v_add_f32_e32 v64, v102, v64
	v_exp_f32_e32 v88, v88
	v_add_f32_e32 v64, v103, v64
	v_exp_f32_e32 v89, v89
	v_add_f32_e32 v64, v85, v64
	v_exp_f32_e32 v90, v90
	v_add_f32_e32 v64, v86, v64
	v_exp_f32_e32 v91, v91
	v_add_f32_e32 v64, v87, v64
	v_exp_f32_e32 v92, v92
	v_add_f32_e32 v64, v88, v64
	v_exp_f32_e32 v93, v93
	v_add_f32_e32 v64, v89, v64
	v_exp_f32_e32 v94, v94
	v_add_f32_e32 v64, v90, v64
	v_fmamk_f32 v77, v77, 0x3e38aa3b, v101
	v_exp_f32_e32 v95, v95
	v_add_f32_e32 v64, v91, v64
	v_fmamk_f32 v78, v78, 0x3e38aa3b, v101
	v_exp_f32_e32 v104, v77
	v_add_f32_e32 v64, v92, v64
	v_fmac_f32_e32 v101, 0x3e38aa3b, v79
	v_exp_f32_e32 v105, v78
	v_add_f32_e32 v64, v93, v64
	v_exp_f32_e32 v101, v101
	v_add_f32_e32 v64, v94, v64
	v_add_f32_e32 v64, v95, v64
	v_add_f32_e32 v64, v104, v64
	v_add_f32_e32 v64, v105, v64
	v_add_f32_e32 v64, v101, v64
	v_mov_b32_e32 v65, v64
	s_nop 1
	v_permlane32_swap_b32_e32 v64, v65
	v_cvt_pk_bf16_f32 v78, v82, v84
	v_cvt_pk_bf16_f32 v79, v80, v83
	v_cvt_pk_bf16_f32 v80, v75, v81
	v_cvt_pk_bf16_f32 v81, v74, v76
	v_cvt_pk_bf16_f32 v74, v71, v73
	v_cvt_pk_bf16_f32 v75, v69, v72
	v_cvt_pk_bf16_f32 v76, v67, v70
	v_cvt_pk_bf16_f32 v77, v66, v68
	v_cvt_pk_bf16_f32 v66, v102, v103
	v_cvt_pk_bf16_f32 v67, v85, v86
	v_cvt_pk_bf16_f32 v68, v87, v88
	v_cvt_pk_bf16_f32 v69, v89, v90
	v_cvt_pk_bf16_f32 v70, v91, v92
	v_cvt_pk_bf16_f32 v71, v93, v94
	v_cvt_pk_bf16_f32 v72, v95, v104
	v_cvt_pk_bf16_f32 v73, v105, v101
	s_nop 0
	v_permlane32_swap_b32_e32 v78, v80
	v_permlane32_swap_b32_e32 v79, v81
	v_permlane32_swap_b32_e32 v74, v76
	v_permlane32_swap_b32_e32 v75, v77
	v_permlane32_swap_b32_e32 v66, v68
	v_permlane32_swap_b32_e32 v67, v69
	v_permlane32_swap_b32_e32 v70, v72
	v_permlane32_swap_b32_e32 v71, v73
	ds_read_b64_tr_b16 v[82:83], v179 offset:0
	ds_read_b64_tr_b16 v[84:85], v179 offset:0x800
	ds_read_b64_tr_b16 v[86:87], v179 offset:0x1000
	ds_read_b64_tr_b16 v[88:89], v179 offset:0x1800
	ds_read_b64_tr_b16 v[90:91], v179 offset:0x2000
	ds_read_b64_tr_b16 v[92:93], v179 offset:0x2800
	ds_read_b64_tr_b16 v[102:103], v179 offset:0x3000
	ds_read_b64_tr_b16 v[104:105], v179 offset:0x3800
	s_waitcnt lgkmcnt(0)
	s_nop 0
	v_mfma_f32_32x32x16_bf16 v[48:63], v[78:81], v[82:85], v[48:63]
	ds_read_b64_tr_b16 v[82:83], v179 offset:0x200
	ds_read_b64_tr_b16 v[84:85], v179 offset:0xa00
	v_mfma_f32_32x32x16_bf16 v[48:63], v[74:77], v[86:89], v[48:63]
	ds_read_b64_tr_b16 v[86:87], v179 offset:0x1200
	ds_read_b64_tr_b16 v[88:89], v179 offset:0x1a00
	v_mfma_f32_32x32x16_bf16 v[48:63], v[66:69], v[90:93], v[48:63]
	ds_read_b64_tr_b16 v[90:91], v179 offset:0x2200
	ds_read_b64_tr_b16 v[92:93], v179 offset:0x2a00
	v_mfma_f32_32x32x16_bf16 v[48:63], v[70:73], v[102:105], v[48:63]
	ds_read_b64_tr_b16 v[102:103], v179 offset:0x3200
	ds_read_b64_tr_b16 v[104:105], v179 offset:0x3a00
	s_waitcnt lgkmcnt(0)
	v_mfma_f32_32x32x16_bf16 v[32:47], v[78:81], v[82:85], v[32:47]
	ds_read_b64_tr_b16 v[82:83], v179 offset:0x400
	ds_read_b64_tr_b16 v[84:85], v179 offset:0xc00
	v_mfma_f32_32x32x16_bf16 v[32:47], v[74:77], v[86:89], v[32:47]
	ds_read_b64_tr_b16 v[86:87], v179 offset:0x1400
	ds_read_b64_tr_b16 v[88:89], v179 offset:0x1c00
	v_mfma_f32_32x32x16_bf16 v[32:47], v[66:69], v[90:93], v[32:47]
	ds_read_b64_tr_b16 v[90:91], v179 offset:0x2400
	ds_read_b64_tr_b16 v[92:93], v179 offset:0x2c00
	v_mfma_f32_32x32x16_bf16 v[32:47], v[70:73], v[102:105], v[32:47]
	ds_read_b64_tr_b16 v[102:103], v179 offset:0x3400
	ds_read_b64_tr_b16 v[104:105], v179 offset:0x3c00
	s_waitcnt lgkmcnt(0)
; __device__ __forceinline__ int crow(int r, int hi) { return (r & 3) + 8 * (r >> 2) + 4 * hi; }
; template <int DQK, int DK1, int LDQ, int LDK, int LDKR, int LDV, int NQL, int SDEPTH>
; __device__ __forceinline__ void attn_core(const AttnArgs& a, char* lds, f32x16 (&o)[4]) {
;     ...
;     if (hi == 0) li_l[r32] = l_reg; asm volatile("s_waitcnt lgkmcnt(0)" ::: "memory");
; #pragma unroll
;     for (int r = 0; r < 16; ++r) { const float rl = __builtin_amdgcn_rcpf(li_l[crow(r, hi)]);
; #pragma unroll
;         for (int d = 0; d < 4; ++d) o[d][r] *= rl; }
;     __syncthreads();
; __device__ __forceinline__ void phase_attn_diff(const Params& p, char* lds) {
;     ...
;             if (j == 0) {
	v_mfma_f32_32x32x16_bf16 v[16:31], v[78:81], v[82:85], v[16:31]
	ds_read_b64_tr_b16 v[82:83], v179 offset:0x600
	ds_read_b64_tr_b16 v[84:85], v179 offset:0xe00
	v_mfma_f32_32x32x16_bf16 v[16:31], v[74:77], v[86:89], v[16:31]
	ds_read_b64_tr_b16 v[86:87], v179 offset:0x1600
	ds_read_b64_tr_b16 v[88:89], v179 offset:0x1e00
	v_mfma_f32_32x32x16_bf16 v[16:31], v[66:69], v[90:93], v[16:31]
	ds_read_b64_tr_b16 v[90:91], v179 offset:0x2600
	ds_read_b64_tr_b16 v[92:93], v179 offset:0x2e00
	v_mfma_f32_32x32x16_bf16 v[16:31], v[70:73], v[102:105], v[16:31]
	ds_read_b64_tr_b16 v[102:103], v179 offset:0x3600
	ds_read_b64_tr_b16 v[104:105], v179 offset:0x3e00
	s_waitcnt lgkmcnt(0)
	v_mfma_f32_32x32x16_bf16 v[0:15], v[78:81], v[82:85], v[0:15]
	v_mfma_f32_32x32x16_bf16 v[0:15], v[74:77], v[86:89], v[0:15]
	v_mfma_f32_32x32x16_bf16 v[0:15], v[66:69], v[90:93], v[0:15]
	v_mfma_f32_32x32x16_bf16 v[0:15], v[70:73], v[102:105], v[0:15]
	s_and_saveexec_b64 s[14:15], s[12:13]
	v_add_f32_e32 v66, v98, v99
	v_fmac_f32_e32 v66, v178, v143
	v_add_f32_e32 v64, v64, v65
	v_fmac_f32_e32 v64, v66, v100
	ds_write_b32 v177, v64 offset:49152
	s_or_b64 exec, exec, s[14:15]
	s_waitcnt lgkmcnt(0)
	v_add_u32_e32 v82, v161, v96
	ds_read_b128 v[74:77], v82 offset:49152
	ds_read_b128 v[78:81], v82 offset:49184
	v_mov_b32_e32 v68, v16
	s_nop 0
	v_mov_b32_e32 v69, v0
	v_mov_b32_e32 v0, v17
	s_waitcnt lgkmcnt(1)
	v_rcp_f32_e32 v16, v75
	v_rcp_f32_e32 v66, v74
	v_mov_b32_e32 v64, v48
	v_mov_b32_e32 v65, v32
	v_pk_mul_f32 v[70:71], v[0:1], v[16:17] op_sel_hi:[1,0]
	v_rcp_f32_e32 v0, v76
	v_mov_b32_e32 v32, v49
	v_pk_mul_f32 v[64:65], v[64:65], v[66:67] op_sel_hi:[1,0]
	v_pk_mul_f32 v[66:67], v[68:69], v[66:67] op_sel_hi:[1,0]
	v_pk_mul_f32 v[68:69], v[32:33], v[16:17] op_sel_hi:[1,0]
	v_mov_b32_e32 v16, v50
	v_mov_b32_e32 v17, v34
	v_pk_mul_f32 v[72:73], v[16:17], v[0:1] op_sel_hi:[1,0]
	v_mov_b32_e32 v16, v18
	v_mov_b32_e32 v17, v2
	v_pk_mul_f32 v[74:75], v[16:17], v[0:1] op_sel_hi:[1,0]
	v_rcp_f32_e32 v16, v77
	v_mov_b32_e32 v32, v20
	s_waitcnt lgkmcnt(0)
	v_rcp_f32_e32 v20, v79
	v_mov_b32_e32 v34, v51
	v_rcp_f32_e32 v18, v78
	v_mov_b32_e32 v33, v4
	v_mov_b32_e32 v4, v21
	v_pk_mul_f32 v[0:1], v[34:35], v[16:17] op_sel_hi:[1,0]
	v_pk_mul_f32 v[34:35], v[4:5], v[20:21] op_sel_hi:[1,0]
	v_rcp_f32_e32 v4, v80
	ds_read_b128 v[76:79], v82 offset:49216
	v_mov_b32_e32 v2, v19
	v_pk_mul_f32 v[2:3], v[2:3], v[16:17] op_sel_hi:[1,0]
	v_mov_b32_e32 v16, v52
	v_mov_b32_e32 v17, v36
	v_mov_b32_e32 v36, v53
	v_pk_mul_f32 v[16:17], v[16:17], v[18:19] op_sel_hi:[1,0]
	v_pk_mul_f32 v[18:19], v[32:33], v[18:19] op_sel_hi:[1,0]
	v_pk_mul_f32 v[32:33], v[36:37], v[20:21] op_sel_hi:[1,0]
	v_mov_b32_e32 v20, v54
	v_mov_b32_e32 v21, v38
	v_pk_mul_f32 v[48:49], v[20:21], v[4:5] op_sel_hi:[1,0]
	v_mov_b32_e32 v20, v22
	v_mov_b32_e32 v21, v6
	v_pk_mul_f32 v[50:51], v[20:21], v[4:5] op_sel_hi:[1,0]
	v_rcp_f32_e32 v20, v81
	v_mov_b32_e32 v36, v24
	s_waitcnt lgkmcnt(0)
	v_rcp_f32_e32 v24, v77
	v_mov_b32_e32 v38, v55
	v_rcp_f32_e32 v22, v76
	v_mov_b32_e32 v37, v8
	v_mov_b32_e32 v8, v25
	v_pk_mul_f32 v[4:5], v[38:39], v[20:21] op_sel_hi:[1,0]
	v_pk_mul_f32 v[38:39], v[8:9], v[24:25] op_sel_hi:[1,0]
	v_rcp_f32_e32 v8, v78
	v_mov_b32_e32 v6, v23
	v_pk_mul_f32 v[6:7], v[6:7], v[20:21] op_sel_hi:[1,0]
	v_mov_b32_e32 v20, v56
	v_mov_b32_e32 v21, v40
	v_mov_b32_e32 v40, v57
	v_pk_mul_f32 v[20:21], v[20:21], v[22:23] op_sel_hi:[1,0]
	v_pk_mul_f32 v[22:23], v[36:37], v[22:23] op_sel_hi:[1,0]
	v_pk_mul_f32 v[36:37], v[40:41], v[24:25] op_sel_hi:[1,0]
	v_mov_b32_e32 v24, v58
	v_mov_b32_e32 v25, v42
	v_pk_mul_f32 v[52:53], v[24:25], v[8:9] op_sel_hi:[1,0]
	v_mov_b32_e32 v24, v26
	v_mov_b32_e32 v25, v10
	v_pk_mul_f32 v[54:55], v[24:25], v[8:9] op_sel_hi:[1,0]
	v_rcp_f32_e32 v24, v79
	ds_read_b128 v[76:79], v82 offset:49248
	v_mov_b32_e32 v40, v28
	v_mov_b32_e32 v42, v59
	v_mov_b32_e32 v41, v12
	v_mov_b32_e32 v12, v29
	s_waitcnt lgkmcnt(0)
	v_rcp_f32_e32 v28, v77
	v_rcp_f32_e32 v26, v76
	v_pk_mul_f32 v[8:9], v[42:43], v[24:25] op_sel_hi:[1,0]
	v_mov_b32_e32 v10, v27
	v_pk_mul_f32 v[42:43], v[12:13], v[28:29] op_sel_hi:[1,0]
	v_rcp_f32_e32 v12, v78
	v_pk_mul_f32 v[10:11], v[10:11], v[24:25] op_sel_hi:[1,0]
	v_mov_b32_e32 v24, v60
	v_mov_b32_e32 v25, v44
	v_mov_b32_e32 v44, v61
	v_pk_mul_f32 v[24:25], v[24:25], v[26:27] op_sel_hi:[1,0]
	v_pk_mul_f32 v[26:27], v[40:41], v[26:27] op_sel_hi:[1,0]
	v_pk_mul_f32 v[40:41], v[44:45], v[28:29] op_sel_hi:[1,0]
	v_mov_b32_e32 v28, v62
	v_mov_b32_e32 v29, v46
	v_pk_mul_f32 v[56:57], v[28:29], v[12:13] op_sel_hi:[1,0]
	v_mov_b32_e32 v28, v30
	v_mov_b32_e32 v29, v14
	v_pk_mul_f32 v[58:59], v[28:29], v[12:13] op_sel_hi:[1,0]
	v_rcp_f32_e32 v28, v79
	v_mov_b32_e32 v46, v63
	v_mov_b32_e32 v14, v31
	s_mov_b64 s[12:13], -1
	v_pk_mul_f32 v[12:13], v[46:47], v[28:29] op_sel_hi:[1,0]
	v_pk_mul_f32 v[14:15], v[14:15], v[28:29] op_sel_hi:[1,0]
	v_mov_b64_e32 v[28:29], v[154:155]
	s_and_b64 vcc, exec, s[94:95]
	s_barrier
	s_cbranch_vccz .LBB0_191
; __device__ __forceinline__ void phase_attn_diff(const Params& p, char* lds) {
;     ...
;             } else {
;                 bf16_t* Ow = O + (size_t)(row0 + wid * 32 + 4 * hi) * 1024 + h * 128 + r32;
;                 asm volatile("" : "+v"(Ow));
; #pragma unroll
;                 for (int r = 0; r < 16; ++r) {
;                     const f32x4 t = *(const f32x4*)(scr + 4 * r);
;                     const float v0 = t[0] - lam * o[0][r], v1 = t[1] - lam * o[1][r], v2 = t[2] - lam * o[2][r], v3 = t[3] - lam * o[3][r];
;                     float ss = v0 * v0 + v1 * v1 + v2 * v2 + v3 * v3;
; #pragma unroll
;                     for (int x = 16; x >= 1; x >>= 1) ss += __shfl_xor(ss, x);
;                     const float rs = rsqrtf(ss * (1.0f / 128.0f) + EPS);
	global_load_dwordx4 v[84:87], v[28:29], off
	global_load_dwordx4 v[88:91], v[28:29], off offset:16
	global_load_dwordx4 v[92:95], v[28:29], off offset:32
	global_load_dwordx4 v[100:103], v[28:29], off offset:48
	global_load_dwordx4 v[104:107], v[28:29], off offset:64
	global_load_dwordx4 v[108:111], v[28:29], off offset:80
	global_load_dwordx4 v[112:115], v[28:29], off offset:96
	global_load_dwordx4 v[116:119], v[28:29], off offset:112
	global_load_dwordx4 v[120:123], v[28:29], off offset:128
	global_load_dwordx4 v[124:127], v[28:29], off offset:144
	global_load_dwordx4 v[128:131], v[28:29], off offset:160
	global_load_dwordx4 v[132:135], v[28:29], off offset:176
	global_load_dwordx4 v[136:139], v[28:29], off offset:192
	global_load_dwordx4 v[140:143], v[28:29], off offset:208
	global_load_dwordx4 v[144:147], v[28:29], off offset:224
	global_load_dwordx4 v[148:151], v[28:29], off offset:240
	v_mov_b64_e32 v[30:31], v[162:163]
	v_xor_b32_e32 v44, 16, v183
	v_xor_b32_e32 v45, 8, v183
	v_xor_b32_e32 v46, 4, v183
	v_xor_b32_e32 v47, 2, v183
	v_xor_b32_e32 v60, 1, v183
	v_lshlrev_b32_e32 v44, 2, v44
	v_lshlrev_b32_e32 v45, 2, v45
	v_lshlrev_b32_e32 v46, 2, v46
	v_lshlrev_b32_e32 v47, 2, v47
	v_lshlrev_b32_e32 v60, 2, v60
	s_mov_b32 s2, 0xd000
	s_waitcnt vmcnt(0) lgkmcnt(0)
	v_pk_fma_f32 v[84:85], v[156:157], v[64:65], v[84:85] neg_lo:[1,0,0] neg_hi:[1,0,0]
	v_pk_fma_f32 v[86:87], v[156:157], v[66:67], v[86:87] neg_lo:[1,0,0] neg_hi:[1,0,0]
	v_pk_fma_f32 v[88:89], v[156:157], v[68:69], v[88:89] neg_lo:[1,0,0] neg_hi:[1,0,0]
	v_pk_fma_f32 v[90:91], v[156:157], v[70:71], v[90:91] neg_lo:[1,0,0] neg_hi:[1,0,0]
	v_pk_fma_f32 v[92:93], v[156:157], v[72:73], v[92:93] neg_lo:[1,0,0] neg_hi:[1,0,0]
	v_pk_fma_f32 v[94:95], v[156:157], v[74:75], v[94:95] neg_lo:[1,0,0] neg_hi:[1,0,0]
	v_pk_fma_f32 v[100:101], v[156:157], v[0:1], v[100:101] neg_lo:[1,0,0] neg_hi:[1,0,0]
	v_pk_fma_f32 v[102:103], v[156:157], v[2:3], v[102:103] neg_lo:[1,0,0] neg_hi:[1,0,0]
	v_pk_fma_f32 v[104:105], v[156:157], v[16:17], v[104:105] neg_lo:[1,0,0] neg_hi:[1,0,0]
	v_pk_fma_f32 v[106:107], v[156:157], v[18:19], v[106:107] neg_lo:[1,0,0] neg_hi:[1,0,0]
	v_pk_fma_f32 v[108:109], v[156:157], v[32:33], v[108:109] neg_lo:[1,0,0] neg_hi:[1,0,0]
	v_pk_fma_f32 v[110:111], v[156:157], v[34:35], v[110:111] neg_lo:[1,0,0] neg_hi:[1,0,0]
	v_pk_fma_f32 v[112:113], v[156:157], v[48:49], v[112:113] neg_lo:[1,0,0] neg_hi:[1,0,0]
	v_pk_fma_f32 v[114:115], v[156:157], v[50:51], v[114:115] neg_lo:[1,0,0] neg_hi:[1,0,0]
	v_pk_fma_f32 v[116:117], v[156:157], v[4:5], v[116:117] neg_lo:[1,0,0] neg_hi:[1,0,0]
	v_pk_fma_f32 v[118:119], v[156:157], v[6:7], v[118:119] neg_lo:[1,0,0] neg_hi:[1,0,0]
	v_pk_fma_f32 v[120:121], v[156:157], v[20:21], v[120:121] neg_lo:[1,0,0] neg_hi:[1,0,0]
	v_pk_fma_f32 v[122:123], v[156:157], v[22:23], v[122:123] neg_lo:[1,0,0] neg_hi:[1,0,0]
	v_pk_fma_f32 v[124:125], v[156:157], v[36:37], v[124:125] neg_lo:[1,0,0] neg_hi:[1,0,0]
	v_pk_fma_f32 v[126:127], v[156:157], v[38:39], v[126:127] neg_lo:[1,0,0] neg_hi:[1,0,0]
	v_pk_fma_f32 v[128:129], v[156:157], v[52:53], v[128:129] neg_lo:[1,0,0] neg_hi:[1,0,0]
	v_pk_fma_f32 v[130:131], v[156:157], v[54:55], v[130:131] neg_lo:[1,0,0] neg_hi:[1,0,0]
	v_pk_fma_f32 v[132:133], v[156:157], v[8:9], v[132:133] neg_lo:[1,0,0] neg_hi:[1,0,0]
	v_pk_fma_f32 v[134:135], v[156:157], v[10:11], v[134:135] neg_lo:[1,0,0] neg_hi:[1,0,0]
	v_pk_fma_f32 v[136:137], v[156:157], v[24:25], v[136:137] neg_lo:[1,0,0] neg_hi:[1,0,0]
	v_pk_fma_f32 v[138:139], v[156:157], v[26:27], v[138:139] neg_lo:[1,0,0] neg_hi:[1,0,0]
	v_pk_fma_f32 v[140:141], v[156:157], v[40:41], v[140:141] neg_lo:[1,0,0] neg_hi:[1,0,0]
	v_pk_fma_f32 v[142:143], v[156:157], v[42:43], v[142:143] neg_lo:[1,0,0] neg_hi:[1,0,0]
	v_pk_fma_f32 v[144:145], v[156:157], v[56:57], v[144:145] neg_lo:[1,0,0] neg_hi:[1,0,0]
	v_pk_fma_f32 v[146:147], v[156:157], v[58:59], v[146:147] neg_lo:[1,0,0] neg_hi:[1,0,0]
	v_pk_fma_f32 v[148:149], v[156:157], v[12:13], v[148:149] neg_lo:[1,0,0] neg_hi:[1,0,0]
	v_pk_fma_f32 v[150:151], v[156:157], v[14:15], v[150:151] neg_lo:[1,0,0] neg_hi:[1,0,0]
	v_pk_mul_f32 v[64:65], v[84:85], v[84:85]
	v_pk_mul_f32 v[66:67], v[86:87], v[86:87]
	v_pk_mul_f32 v[68:69], v[88:89], v[88:89]
	v_pk_mul_f32 v[70:71], v[90:91], v[90:91]
	v_pk_mul_f32 v[72:73], v[92:93], v[92:93]
	v_pk_mul_f32 v[74:75], v[94:95], v[94:95]
	v_pk_mul_f32 v[0:1], v[100:101], v[100:101]
	v_pk_mul_f32 v[2:3], v[102:103], v[102:103]
	v_pk_mul_f32 v[16:17], v[104:105], v[104:105]
	v_pk_mul_f32 v[18:19], v[106:107], v[106:107]
	v_pk_mul_f32 v[32:33], v[108:109], v[108:109]
	v_pk_mul_f32 v[34:35], v[110:111], v[110:111]
	v_pk_mul_f32 v[48:49], v[112:113], v[112:113]
	v_pk_mul_f32 v[50:51], v[114:115], v[114:115]
	v_pk_mul_f32 v[4:5], v[116:117], v[116:117]
	v_pk_mul_f32 v[6:7], v[118:119], v[118:119]
	v_pk_mul_f32 v[20:21], v[120:121], v[120:121]
	v_pk_mul_f32 v[22:23], v[122:123], v[122:123]
	v_pk_mul_f32 v[36:37], v[124:125], v[124:125]
	v_pk_mul_f32 v[38:39], v[126:127], v[126:127]
	v_pk_mul_f32 v[52:53], v[128:129], v[128:129]
	v_pk_mul_f32 v[54:55], v[130:131], v[130:131]
	v_pk_mul_f32 v[8:9], v[132:133], v[132:133]
	v_pk_mul_f32 v[10:11], v[134:135], v[134:135]
	v_pk_mul_f32 v[24:25], v[136:137], v[136:137]
	v_pk_mul_f32 v[26:27], v[138:139], v[138:139]
	v_pk_mul_f32 v[40:41], v[140:141], v[140:141]
	v_pk_mul_f32 v[42:43], v[142:143], v[142:143]
	v_pk_mul_f32 v[56:57], v[144:145], v[144:145]
	v_pk_mul_f32 v[58:59], v[146:147], v[146:147]
	v_pk_mul_f32 v[12:13], v[148:149], v[148:149]
	v_pk_mul_f32 v[14:15], v[150:151], v[150:151]
	v_add_f32_e32 v64, v64, v65
	v_add_f32_e32 v68, v68, v69
; __device__ __forceinline__ void phase_attn_diff(const Params& p, char* lds) {
;     ...
;                     float ss = v0 * v0 + v1 * v1 + v2 * v2 + v3 * v3;
; #pragma unroll
;                     for (int x = 16; x >= 1; x >>= 1) ss += __shfl_xor(ss, x);
	v_add_f32_e32 v72, v72, v73
	v_add_f32_e32 v0, v0, v1
	v_add_f32_e32 v16, v16, v17
	v_add_f32_e32 v32, v32, v33
	v_add_f32_e32 v48, v48, v49
	v_add_f32_e32 v4, v4, v5
	v_add_f32_e32 v20, v20, v21
	v_add_f32_e32 v36, v36, v37
	v_add_f32_e32 v52, v52, v53
	v_add_f32_e32 v8, v8, v9
	v_add_f32_e32 v24, v24, v25
	v_add_f32_e32 v40, v40, v41
	v_add_f32_e32 v56, v56, v57
	v_add_f32_e32 v12, v12, v13
	v_add_f32_e32 v64, v66, v64
	v_add_f32_e32 v68, v70, v68
	v_add_f32_e32 v72, v74, v72
	v_add_f32_e32 v0, v2, v0
	v_add_f32_e32 v16, v18, v16
	v_add_f32_e32 v32, v34, v32
	v_add_f32_e32 v48, v50, v48
	v_add_f32_e32 v4, v6, v4
	v_add_f32_e32 v20, v22, v20
	v_add_f32_e32 v36, v38, v36
	v_add_f32_e32 v52, v54, v52
	v_add_f32_e32 v8, v10, v8
	v_add_f32_e32 v24, v26, v24
	v_add_f32_e32 v40, v42, v40
	v_add_f32_e32 v56, v58, v56
	v_add_f32_e32 v12, v14, v12
	v_add_f32_e32 v64, v67, v64
	v_add_f32_e32 v68, v71, v68
	v_add_f32_e32 v72, v75, v72
	v_add_f32_e32 v0, v3, v0
	v_add_f32_e32 v16, v19, v16
	v_add_f32_e32 v32, v35, v32
	v_add_f32_e32 v48, v51, v48
	v_add_f32_e32 v4, v7, v4
	v_add_f32_e32 v20, v23, v20
	v_add_f32_e32 v36, v39, v36
	v_add_f32_e32 v52, v55, v52
	v_add_f32_e32 v8, v11, v8
	v_add_f32_e32 v24, v27, v24
	v_add_f32_e32 v40, v43, v40
	v_add_f32_e32 v56, v59, v56
	v_add_f32_e32 v12, v15, v12
	ds_bpermute_b32 v65, v44, v64
	ds_bpermute_b32 v69, v44, v68
	ds_bpermute_b32 v73, v44, v72
	ds_bpermute_b32 v1, v44, v0
	ds_bpermute_b32 v17, v44, v16
	ds_bpermute_b32 v33, v44, v32
	ds_bpermute_b32 v49, v44, v48
	ds_bpermute_b32 v5, v44, v4
	ds_bpermute_b32 v21, v44, v20
	ds_bpermute_b32 v37, v44, v36
	ds_bpermute_b32 v53, v44, v52
	ds_bpermute_b32 v9, v44, v8
	ds_bpermute_b32 v25, v44, v24
	ds_bpermute_b32 v41, v44, v40
	ds_bpermute_b32 v57, v44, v56
	ds_bpermute_b32 v13, v44, v12
	s_waitcnt lgkmcnt(15)
	v_add_f32_e32 v64, v64, v65
	s_waitcnt lgkmcnt(14)
	v_add_f32_e32 v68, v68, v69
	s_waitcnt lgkmcnt(13)
	v_add_f32_e32 v72, v72, v73
	s_waitcnt lgkmcnt(12)
	v_add_f32_e32 v0, v0, v1
	s_waitcnt lgkmcnt(11)
	v_add_f32_e32 v16, v16, v17
	s_waitcnt lgkmcnt(10)
	v_add_f32_e32 v32, v32, v33
	s_waitcnt lgkmcnt(9)
	v_add_f32_e32 v48, v48, v49
	s_waitcnt lgkmcnt(8)
	v_add_f32_e32 v4, v4, v5
	s_waitcnt lgkmcnt(7)
	v_add_f32_e32 v20, v20, v21
	s_waitcnt lgkmcnt(6)
	v_add_f32_e32 v36, v36, v37
	s_waitcnt lgkmcnt(5)
	v_add_f32_e32 v52, v52, v53
	s_waitcnt lgkmcnt(4)
	v_add_f32_e32 v8, v8, v9
	s_waitcnt lgkmcnt(3)
	v_add_f32_e32 v24, v24, v25
	s_waitcnt lgkmcnt(2)
	v_add_f32_e32 v40, v40, v41
	s_waitcnt lgkmcnt(1)
	v_add_f32_e32 v56, v56, v57
	s_waitcnt lgkmcnt(0)
	v_add_f32_e32 v12, v12, v13
	ds_bpermute_b32 v65, v45, v64
	ds_bpermute_b32 v69, v45, v68
	ds_bpermute_b32 v73, v45, v72
	ds_bpermute_b32 v1, v45, v0
	ds_bpermute_b32 v17, v45, v16
	ds_bpermute_b32 v33, v45, v32
	ds_bpermute_b32 v49, v45, v48
	ds_bpermute_b32 v5, v45, v4
	ds_bpermute_b32 v21, v45, v20
	ds_bpermute_b32 v37, v45, v36
	ds_bpermute_b32 v53, v45, v52
	ds_bpermute_b32 v9, v45, v8
	ds_bpermute_b32 v25, v45, v24
	ds_bpermute_b32 v41, v45, v40
	ds_bpermute_b32 v57, v45, v56
	ds_bpermute_b32 v13, v45, v12
	s_waitcnt lgkmcnt(15)
	v_add_f32_e32 v64, v64, v65
	s_waitcnt lgkmcnt(14)
	v_add_f32_e32 v68, v68, v69
	s_waitcnt lgkmcnt(13)
	v_add_f32_e32 v72, v72, v73
	s_waitcnt lgkmcnt(12)
	v_add_f32_e32 v0, v0, v1
	s_waitcnt lgkmcnt(11)
	v_add_f32_e32 v16, v16, v17
	s_waitcnt lgkmcnt(10)
	v_add_f32_e32 v32, v32, v33
	s_waitcnt lgkmcnt(9)
	v_add_f32_e32 v48, v48, v49
	s_waitcnt lgkmcnt(8)
	v_add_f32_e32 v4, v4, v5
	s_waitcnt lgkmcnt(7)
	v_add_f32_e32 v20, v20, v21
	s_waitcnt lgkmcnt(6)
	v_add_f32_e32 v36, v36, v37
	s_waitcnt lgkmcnt(5)
	v_add_f32_e32 v52, v52, v53
	s_waitcnt lgkmcnt(4)
	v_add_f32_e32 v8, v8, v9
	s_waitcnt lgkmcnt(3)
	v_add_f32_e32 v24, v24, v25
	s_waitcnt lgkmcnt(2)
	v_add_f32_e32 v40, v40, v41
	s_waitcnt lgkmcnt(1)
	v_add_f32_e32 v56, v56, v57
	s_waitcnt lgkmcnt(0)
	v_add_f32_e32 v12, v12, v13
	ds_bpermute_b32 v65, v46, v64
	ds_bpermute_b32 v69, v46, v68
	ds_bpermute_b32 v73, v46, v72
	ds_bpermute_b32 v1, v46, v0
	ds_bpermute_b32 v17, v46, v16
	ds_bpermute_b32 v33, v46, v32
	ds_bpermute_b32 v49, v46, v48
	ds_bpermute_b32 v5, v46, v4
	ds_bpermute_b32 v21, v46, v20
	ds_bpermute_b32 v37, v46, v36
	ds_bpermute_b32 v53, v46, v52
	ds_bpermute_b32 v9, v46, v8
	ds_bpermute_b32 v25, v46, v24
	ds_bpermute_b32 v41, v46, v40
	ds_bpermute_b32 v57, v46, v56
	ds_bpermute_b32 v13, v46, v12
	s_waitcnt lgkmcnt(15)
	v_add_f32_e32 v64, v64, v65
	s_waitcnt lgkmcnt(14)
	v_add_f32_e32 v68, v68, v69
	s_waitcnt lgkmcnt(13)
	v_add_f32_e32 v72, v72, v73
	s_waitcnt lgkmcnt(12)
	v_add_f32_e32 v0, v0, v1
	s_waitcnt lgkmcnt(11)
	v_add_f32_e32 v16, v16, v17
	s_waitcnt lgkmcnt(10)
	v_add_f32_e32 v32, v32, v33
	s_waitcnt lgkmcnt(9)
	v_add_f32_e32 v48, v48, v49
	s_waitcnt lgkmcnt(8)
	v_add_f32_e32 v4, v4, v5
	s_waitcnt lgkmcnt(7)
	v_add_f32_e32 v20, v20, v21
	s_waitcnt lgkmcnt(6)
	v_add_f32_e32 v36, v36, v37
	s_waitcnt lgkmcnt(5)
	v_add_f32_e32 v52, v52, v53
	s_waitcnt lgkmcnt(4)
	v_add_f32_e32 v8, v8, v9
	s_waitcnt lgkmcnt(3)
	v_add_f32_e32 v24, v24, v25
	s_waitcnt lgkmcnt(2)
	v_add_f32_e32 v40, v40, v41
	s_waitcnt lgkmcnt(1)
	v_add_f32_e32 v56, v56, v57
	s_waitcnt lgkmcnt(0)
	v_add_f32_e32 v12, v12, v13
	ds_bpermute_b32 v65, v47, v64
	ds_bpermute_b32 v69, v47, v68
	ds_bpermute_b32 v73, v47, v72
	ds_bpermute_b32 v1, v47, v0
	ds_bpermute_b32 v17, v47, v16
	ds_bpermute_b32 v33, v47, v32
	ds_bpermute_b32 v49, v47, v48
	ds_bpermute_b32 v5, v47, v4
	ds_bpermute_b32 v21, v47, v20
	ds_bpermute_b32 v37, v47, v36
	ds_bpermute_b32 v53, v47, v52
	ds_bpermute_b32 v9, v47, v8
	ds_bpermute_b32 v25, v47, v24
	ds_bpermute_b32 v41, v47, v40
	ds_bpermute_b32 v57, v47, v56
	ds_bpermute_b32 v13, v47, v12
	s_waitcnt lgkmcnt(15)
; __device__ __forceinline__ void phase_attn_diff(const Params& p, char* lds) {
;     ...
;                     for (int x = 16; x >= 1; x >>= 1) ss += __shfl_xor(ss, x);
;                     const float rs = rsqrtf(ss * (1.0f / 128.0f) + EPS);
	v_add_f32_e32 v64, v64, v65
	s_waitcnt lgkmcnt(14)
	v_add_f32_e32 v68, v68, v69
	s_waitcnt lgkmcnt(13)
	v_add_f32_e32 v72, v72, v73
	s_waitcnt lgkmcnt(12)
	v_add_f32_e32 v0, v0, v1
	s_waitcnt lgkmcnt(11)
	v_add_f32_e32 v16, v16, v17
	s_waitcnt lgkmcnt(10)
	v_add_f32_e32 v32, v32, v33
	s_waitcnt lgkmcnt(9)
	v_add_f32_e32 v48, v48, v49
	s_waitcnt lgkmcnt(8)
	v_add_f32_e32 v4, v4, v5
	s_waitcnt lgkmcnt(7)
	v_add_f32_e32 v20, v20, v21
	s_waitcnt lgkmcnt(6)
	v_add_f32_e32 v36, v36, v37
	s_waitcnt lgkmcnt(5)
	v_add_f32_e32 v52, v52, v53
	s_waitcnt lgkmcnt(4)
	v_add_f32_e32 v8, v8, v9
	s_waitcnt lgkmcnt(3)
	v_add_f32_e32 v24, v24, v25
	s_waitcnt lgkmcnt(2)
	v_add_f32_e32 v40, v40, v41
	s_waitcnt lgkmcnt(1)
	v_add_f32_e32 v56, v56, v57
	s_waitcnt lgkmcnt(0)
	v_add_f32_e32 v12, v12, v13
	ds_bpermute_b32 v65, v60, v64
	ds_bpermute_b32 v69, v60, v68
	ds_bpermute_b32 v73, v60, v72
	ds_bpermute_b32 v1, v60, v0
	ds_bpermute_b32 v17, v60, v16
	ds_bpermute_b32 v33, v60, v32
	ds_bpermute_b32 v49, v60, v48
	ds_bpermute_b32 v5, v60, v4
	ds_bpermute_b32 v21, v60, v20
	ds_bpermute_b32 v37, v60, v36
	ds_bpermute_b32 v53, v60, v52
	ds_bpermute_b32 v9, v60, v8
	ds_bpermute_b32 v25, v60, v24
	ds_bpermute_b32 v41, v60, v40
	ds_bpermute_b32 v57, v60, v56
	ds_bpermute_b32 v13, v60, v12
	s_waitcnt lgkmcnt(15)
	v_add_f32_e32 v64, v64, v65
	s_waitcnt lgkmcnt(14)
	v_add_f32_e32 v68, v68, v69
	s_waitcnt lgkmcnt(13)
	v_add_f32_e32 v72, v72, v73
	s_waitcnt lgkmcnt(12)
	v_add_f32_e32 v0, v0, v1
	s_waitcnt lgkmcnt(11)
	v_add_f32_e32 v16, v16, v17
	s_waitcnt lgkmcnt(10)
	v_add_f32_e32 v32, v32, v33
	s_waitcnt lgkmcnt(9)
	v_add_f32_e32 v48, v48, v49
	s_waitcnt lgkmcnt(8)
	v_add_f32_e32 v4, v4, v5
	s_waitcnt lgkmcnt(7)
	v_add_f32_e32 v20, v20, v21
	s_waitcnt lgkmcnt(6)
	v_add_f32_e32 v36, v36, v37
	s_waitcnt lgkmcnt(5)
	v_add_f32_e32 v52, v52, v53
	s_waitcnt lgkmcnt(4)
	v_add_f32_e32 v8, v8, v9
	s_waitcnt lgkmcnt(3)
	v_add_f32_e32 v24, v24, v25
	s_waitcnt lgkmcnt(2)
	v_add_f32_e32 v40, v40, v41
	s_waitcnt lgkmcnt(1)
	v_add_f32_e32 v56, v56, v57
	s_waitcnt lgkmcnt(0)
	v_add_f32_e32 v12, v12, v13
	v_fmamk_f32 v64, v64, 0x3c000000, v158
	v_cmp_gt_f32_e32 vcc, s82, v64
	v_mul_f32_e32 v65, 0x4b800000, v64
	s_nop 0
	v_cndmask_b32_e32 v64, v64, v65, vcc
	v_rsq_f32_e32 v64, v64
	s_nop 0
	v_mul_f32_e32 v65, 0x45800000, v64
	v_cndmask_b32_e32 v64, v64, v65, vcc
	v_fmamk_f32 v68, v68, 0x3c000000, v158
	v_cmp_gt_f32_e32 vcc, s82, v68
	v_mul_f32_e32 v69, 0x4b800000, v68
	s_nop 0
	v_cndmask_b32_e32 v68, v68, v69, vcc
	v_rsq_f32_e32 v68, v68
	s_nop 0
	v_mul_f32_e32 v69, 0x45800000, v68
	v_cndmask_b32_e32 v68, v68, v69, vcc
	v_fmamk_f32 v72, v72, 0x3c000000, v158
	v_cmp_gt_f32_e32 vcc, s82, v72
	v_mul_f32_e32 v73, 0x4b800000, v72
	s_nop 0
	v_cndmask_b32_e32 v72, v72, v73, vcc
	v_rsq_f32_e32 v72, v72
	s_nop 0
	v_mul_f32_e32 v73, 0x45800000, v72
	v_cndmask_b32_e32 v72, v72, v73, vcc
	v_fmamk_f32 v0, v0, 0x3c000000, v158
	v_cmp_gt_f32_e32 vcc, s82, v0
	v_mul_f32_e32 v1, 0x4b800000, v0
	s_nop 0
	v_cndmask_b32_e32 v0, v0, v1, vcc
	v_rsq_f32_e32 v0, v0
	s_nop 0
	v_mul_f32_e32 v1, 0x45800000, v0
	v_cndmask_b32_e32 v0, v0, v1, vcc
	v_fmamk_f32 v16, v16, 0x3c000000, v158
	v_cmp_gt_f32_e32 vcc, s82, v16
	v_mul_f32_e32 v17, 0x4b800000, v16
	s_nop 0
	v_cndmask_b32_e32 v16, v16, v17, vcc
	v_rsq_f32_e32 v16, v16
	s_nop 0
	v_mul_f32_e32 v17, 0x45800000, v16
	v_cndmask_b32_e32 v16, v16, v17, vcc
	v_fmamk_f32 v32, v32, 0x3c000000, v158
	v_cmp_gt_f32_e32 vcc, s82, v32
	v_mul_f32_e32 v33, 0x4b800000, v32
	s_nop 0
	v_cndmask_b32_e32 v32, v32, v33, vcc
	v_rsq_f32_e32 v32, v32
	s_nop 0
	v_mul_f32_e32 v33, 0x45800000, v32
	v_cndmask_b32_e32 v32, v32, v33, vcc
	v_fmamk_f32 v48, v48, 0x3c000000, v158
	v_cmp_gt_f32_e32 vcc, s82, v48
	v_mul_f32_e32 v49, 0x4b800000, v48
	s_nop 0
	v_cndmask_b32_e32 v48, v48, v49, vcc
	v_rsq_f32_e32 v48, v48
	s_nop 0
	v_mul_f32_e32 v49, 0x45800000, v48
	v_cndmask_b32_e32 v48, v48, v49, vcc
	v_fmamk_f32 v4, v4, 0x3c000000, v158
	v_cmp_gt_f32_e32 vcc, s82, v4
	v_mul_f32_e32 v5, 0x4b800000, v4
	s_nop 0
	v_cndmask_b32_e32 v4, v4, v5, vcc
	v_rsq_f32_e32 v4, v4
	s_nop 0
	v_mul_f32_e32 v5, 0x45800000, v4
	v_cndmask_b32_e32 v4, v4, v5, vcc
	v_fmamk_f32 v20, v20, 0x3c000000, v158
	v_cmp_gt_f32_e32 vcc, s82, v20
	v_mul_f32_e32 v21, 0x4b800000, v20
	s_nop 0
	v_cndmask_b32_e32 v20, v20, v21, vcc
	v_rsq_f32_e32 v20, v20
	s_nop 0
	v_mul_f32_e32 v21, 0x45800000, v20
	v_cndmask_b32_e32 v20, v20, v21, vcc
	v_fmamk_f32 v36, v36, 0x3c000000, v158
	v_cmp_gt_f32_e32 vcc, s82, v36
	v_mul_f32_e32 v37, 0x4b800000, v36
	s_nop 0
	v_cndmask_b32_e32 v36, v36, v37, vcc
	v_rsq_f32_e32 v36, v36
	s_nop 0
	v_mul_f32_e32 v37, 0x45800000, v36
	v_cndmask_b32_e32 v36, v36, v37, vcc
	v_fmamk_f32 v52, v52, 0x3c000000, v158
	v_cmp_gt_f32_e32 vcc, s82, v52
	v_mul_f32_e32 v53, 0x4b800000, v52
	s_nop 0
	v_cndmask_b32_e32 v52, v52, v53, vcc
	v_rsq_f32_e32 v52, v52
	s_nop 0
	v_mul_f32_e32 v53, 0x45800000, v52
	v_cndmask_b32_e32 v52, v52, v53, vcc
	v_fmamk_f32 v8, v8, 0x3c000000, v158
	v_cmp_gt_f32_e32 vcc, s82, v8
	v_mul_f32_e32 v9, 0x4b800000, v8
	s_nop 0
	v_cndmask_b32_e32 v8, v8, v9, vcc
	v_rsq_f32_e32 v8, v8
	s_nop 0
	v_mul_f32_e32 v9, 0x45800000, v8
	v_cndmask_b32_e32 v8, v8, v9, vcc
	v_fmamk_f32 v24, v24, 0x3c000000, v158
	v_cmp_gt_f32_e32 vcc, s82, v24
	v_mul_f32_e32 v25, 0x4b800000, v24
	s_nop 0
	v_cndmask_b32_e32 v24, v24, v25, vcc
	v_rsq_f32_e32 v24, v24
	s_nop 0
	v_mul_f32_e32 v25, 0x45800000, v24
	v_cndmask_b32_e32 v24, v24, v25, vcc
	v_fmamk_f32 v40, v40, 0x3c000000, v158
	v_cmp_gt_f32_e32 vcc, s82, v40
	v_mul_f32_e32 v41, 0x4b800000, v40
	s_nop 0
	v_cndmask_b32_e32 v40, v40, v41, vcc
	v_rsq_f32_e32 v40, v40
	s_nop 0
; __device__ __forceinline__ unsigned cvt_pk_bf16(float lo, float hi) { unsigned r; asm volatile("v_cvt_pk_bf16_f32 %0, %1, %2" : "=v"(r) : "v"(lo), "v"(hi)); return r; }
; __device__ __forceinline__ void phase_attn_diff(const Params& p, char* lds) {
;     ...
;                     bf16_t* Or = Ow + (size_t)((r & 3) + 8 * (r >> 2)) * 1024;
;                     Or[0] = (bf16_t)(cvt_pk_bf16(v0 * rs * gs[0], 0.f) & 0xffffu); Or[32] = (bf16_t)(cvt_pk_bf16(v1 * rs * gs[1], 0.f) & 0xffffu);
;                     Or[64] = (bf16_t)(cvt_pk_bf16(v2 * rs * gs[2], 0.f) & 0xffffu); Or[96] = (bf16_t)(cvt_pk_bf16(v3 * rs * gs[3], 0.f) & 0xffffu);
	v_mul_f32_e32 v41, 0x45800000, v40
	v_cndmask_b32_e32 v40, v40, v41, vcc
	v_fmamk_f32 v56, v56, 0x3c000000, v158
	v_cmp_gt_f32_e32 vcc, s82, v56
	v_mul_f32_e32 v57, 0x4b800000, v56
	s_nop 0
	v_cndmask_b32_e32 v56, v56, v57, vcc
	v_rsq_f32_e32 v56, v56
	s_nop 0
	v_mul_f32_e32 v57, 0x45800000, v56
	v_cndmask_b32_e32 v56, v56, v57, vcc
	v_fmamk_f32 v12, v12, 0x3c000000, v158
	v_cmp_gt_f32_e32 vcc, s82, v12
	v_mul_f32_e32 v13, 0x4b800000, v12
	s_nop 0
	v_cndmask_b32_e32 v12, v12, v13, vcc
	v_rsq_f32_e32 v12, v12
	s_nop 0
	v_mul_f32_e32 v13, 0x45800000, v12
	v_cndmask_b32_e32 v12, v12, v13, vcc
	v_add_co_u32_e32 v66, vcc, s83, v30
	s_nop 1
	v_addc_co_u32_e32 v67, vcc, 0, v31, vcc
	v_add_co_u32_e32 v70, vcc, s54, v30
	s_nop 1
	v_addc_co_u32_e32 v71, vcc, 0, v31, vcc
	v_add_co_u32_e32 v74, vcc, s59, v30
	s_nop 1
	v_addc_co_u32_e32 v75, vcc, 0, v31, vcc
	v_add_co_u32_e32 v2, vcc, s67, v30
	s_nop 1
	v_addc_co_u32_e32 v3, vcc, 0, v31, vcc
	v_add_co_u32_e32 v18, vcc, s55, v30
	s_nop 1
	v_addc_co_u32_e32 v19, vcc, 0, v31, vcc
	v_add_co_u32_e32 v34, vcc, s58, v30
	s_nop 1
	v_addc_co_u32_e32 v35, vcc, 0, v31, vcc
	v_add_co_u32_e32 v50, vcc, s2, v30
	s_nop 1
	v_addc_co_u32_e32 v51, vcc, 0, v31, vcc
	v_mul_f32_e32 v84, v84, v64
	v_mul_f32_e32 v85, v85, v64
	v_mul_f32_e32 v86, v86, v64
	v_mul_f32_e32 v87, v87, v64
	v_mul_f32_e32 v88, v88, v68
	v_mul_f32_e32 v89, v89, v68
	v_mul_f32_e32 v90, v90, v68
	v_mul_f32_e32 v91, v91, v68
	v_mul_f32_e32 v92, v92, v72
	v_mul_f32_e32 v93, v93, v72
	v_mul_f32_e32 v94, v94, v72
	v_mul_f32_e32 v95, v95, v72
	v_mul_f32_e32 v100, v100, v0
	v_mul_f32_e32 v101, v101, v0
	v_mul_f32_e32 v102, v102, v0
	v_mul_f32_e32 v103, v103, v0
	v_mul_f32_e32 v104, v104, v16
	v_mul_f32_e32 v105, v105, v16
	v_mul_f32_e32 v106, v106, v16
	v_mul_f32_e32 v107, v107, v16
	v_mul_f32_e32 v108, v108, v32
	v_mul_f32_e32 v109, v109, v32
	v_mul_f32_e32 v110, v110, v32
	v_mul_f32_e32 v111, v111, v32
	v_mul_f32_e32 v112, v112, v48
	v_mul_f32_e32 v113, v113, v48
	v_mul_f32_e32 v114, v114, v48
	v_mul_f32_e32 v115, v115, v48
	v_mul_f32_e32 v116, v116, v4
	v_mul_f32_e32 v117, v117, v4
	v_mul_f32_e32 v118, v118, v4
	v_mul_f32_e32 v119, v119, v4
	v_mul_f32_e32 v120, v120, v20
	v_mul_f32_e32 v121, v121, v20
	v_mul_f32_e32 v122, v122, v20
	v_mul_f32_e32 v123, v123, v20
	v_mul_f32_e32 v124, v124, v36
	v_mul_f32_e32 v125, v125, v36
	v_mul_f32_e32 v126, v126, v36
	v_mul_f32_e32 v127, v127, v36
	v_mul_f32_e32 v128, v128, v52
	v_mul_f32_e32 v129, v129, v52
	v_mul_f32_e32 v130, v130, v52
	v_mul_f32_e32 v131, v131, v52
	v_mul_f32_e32 v132, v132, v8
	v_mul_f32_e32 v133, v133, v8
	v_mul_f32_e32 v134, v134, v8
	v_mul_f32_e32 v135, v135, v8
	v_mul_f32_e32 v136, v136, v24
	v_mul_f32_e32 v137, v137, v24
	v_mul_f32_e32 v138, v138, v24
	v_mul_f32_e32 v139, v139, v24
	v_mul_f32_e32 v140, v140, v40
	v_mul_f32_e32 v141, v141, v40
	v_mul_f32_e32 v142, v142, v40
	v_mul_f32_e32 v143, v143, v40
	v_mul_f32_e32 v144, v144, v56
	v_mul_f32_e32 v145, v145, v56
	v_mul_f32_e32 v146, v146, v56
	v_mul_f32_e32 v147, v147, v56
	v_mul_f32_e32 v148, v148, v12
	v_mul_f32_e32 v149, v149, v12
	v_mul_f32_e32 v150, v150, v12
	v_mul_f32_e32 v151, v151, v12
	v_mul_f32_e32 v84, v172, v84
	v_mul_f32_e32 v85, v173, v85
	v_mul_f32_e32 v86, v174, v86
	v_mul_f32_e32 v87, v175, v87
	v_mul_f32_e32 v88, v172, v88
	v_mul_f32_e32 v89, v173, v89
	v_mul_f32_e32 v90, v174, v90
	v_mul_f32_e32 v91, v175, v91
	v_mul_f32_e32 v92, v172, v92
	v_mul_f32_e32 v93, v173, v93
	v_mul_f32_e32 v94, v174, v94
	v_mul_f32_e32 v95, v175, v95
	v_mul_f32_e32 v100, v172, v100
	v_mul_f32_e32 v101, v173, v101
	v_mul_f32_e32 v102, v174, v102
	v_mul_f32_e32 v103, v175, v103
	v_mul_f32_e32 v104, v172, v104
	v_mul_f32_e32 v105, v173, v105
	v_mul_f32_e32 v106, v174, v106
	v_mul_f32_e32 v107, v175, v107
	v_mul_f32_e32 v108, v172, v108
	v_mul_f32_e32 v109, v173, v109
	v_mul_f32_e32 v110, v174, v110
	v_mul_f32_e32 v111, v175, v111
	v_mul_f32_e32 v112, v172, v112
	v_mul_f32_e32 v113, v173, v113
	v_mul_f32_e32 v114, v174, v114
	v_mul_f32_e32 v115, v175, v115
	v_mul_f32_e32 v116, v172, v116
	v_mul_f32_e32 v117, v173, v117
	v_mul_f32_e32 v118, v174, v118
	v_mul_f32_e32 v119, v175, v119
	v_mul_f32_e32 v120, v172, v120
	v_mul_f32_e32 v121, v173, v121
	v_mul_f32_e32 v122, v174, v122
	v_mul_f32_e32 v123, v175, v123
	v_mul_f32_e32 v124, v172, v124
	v_mul_f32_e32 v125, v173, v125
	v_mul_f32_e32 v126, v174, v126
	v_mul_f32_e32 v127, v175, v127
	v_mul_f32_e32 v128, v172, v128
	v_mul_f32_e32 v129, v173, v129
	v_mul_f32_e32 v130, v174, v130
	v_mul_f32_e32 v131, v175, v131
	v_mul_f32_e32 v132, v172, v132
	v_mul_f32_e32 v133, v173, v133
	v_mul_f32_e32 v134, v174, v134
	v_mul_f32_e32 v135, v175, v135
	v_mul_f32_e32 v136, v172, v136
	v_mul_f32_e32 v137, v173, v137
	v_mul_f32_e32 v138, v174, v138
	v_mul_f32_e32 v139, v175, v139
	v_mul_f32_e32 v140, v172, v140
	v_mul_f32_e32 v141, v173, v141
	v_mul_f32_e32 v142, v174, v142
	v_mul_f32_e32 v143, v175, v143
	v_mul_f32_e32 v144, v172, v144
	v_mul_f32_e32 v145, v173, v145
	v_mul_f32_e32 v146, v174, v146
	v_mul_f32_e32 v147, v175, v147
	v_mul_f32_e32 v148, v172, v148
	v_mul_f32_e32 v149, v173, v149
	v_mul_f32_e32 v150, v174, v150
	v_mul_f32_e32 v151, v175, v151
	v_cvt_pk_bf16_f32 v84, v84, v97
	v_cvt_pk_bf16_f32 v85, v85, v97
	v_cvt_pk_bf16_f32 v86, v86, v97
	v_cvt_pk_bf16_f32 v87, v87, v97
; __device__ __forceinline__ unsigned cvt_pk_bf16(float lo, float hi) { unsigned r; asm volatile("v_cvt_pk_bf16_f32 %0, %1, %2" : "=v"(r) : "v"(lo), "v"(hi)); return r; }
; __device__ __forceinline__ void phase_attn_diff(const Params& p, char* lds) {
;     ...
;                     Or[0] = (bf16_t)(cvt_pk_bf16(v0 * rs * gs[0], 0.f) & 0xffffu); Or[32] = (bf16_t)(cvt_pk_bf16(v1 * rs * gs[1], 0.f) & 0xffffu);
;                     Or[64] = (bf16_t)(cvt_pk_bf16(v2 * rs * gs[2], 0.f) & 0xffffu); Or[96] = (bf16_t)(cvt_pk_bf16(v3 * rs * gs[3], 0.f) & 0xffffu);
	v_cvt_pk_bf16_f32 v88, v88, v97
	v_cvt_pk_bf16_f32 v89, v89, v97
	v_cvt_pk_bf16_f32 v90, v90, v97
	v_cvt_pk_bf16_f32 v91, v91, v97
	v_cvt_pk_bf16_f32 v92, v92, v97
	v_cvt_pk_bf16_f32 v93, v93, v97
	v_cvt_pk_bf16_f32 v94, v94, v97
	v_cvt_pk_bf16_f32 v95, v95, v97
	v_cvt_pk_bf16_f32 v100, v100, v97
	v_cvt_pk_bf16_f32 v101, v101, v97
	v_cvt_pk_bf16_f32 v102, v102, v97
	v_cvt_pk_bf16_f32 v103, v103, v97
	v_cvt_pk_bf16_f32 v104, v104, v97
	v_cvt_pk_bf16_f32 v105, v105, v97
	v_cvt_pk_bf16_f32 v106, v106, v97
	v_cvt_pk_bf16_f32 v107, v107, v97
	v_cvt_pk_bf16_f32 v108, v108, v97
	v_cvt_pk_bf16_f32 v109, v109, v97
	v_cvt_pk_bf16_f32 v110, v110, v97
	v_cvt_pk_bf16_f32 v111, v111, v97
	v_cvt_pk_bf16_f32 v112, v112, v97
	v_cvt_pk_bf16_f32 v113, v113, v97
	v_cvt_pk_bf16_f32 v114, v114, v97
	v_cvt_pk_bf16_f32 v115, v115, v97
	v_cvt_pk_bf16_f32 v116, v116, v97
	v_cvt_pk_bf16_f32 v117, v117, v97
	v_cvt_pk_bf16_f32 v118, v118, v97
	v_cvt_pk_bf16_f32 v119, v119, v97
	v_cvt_pk_bf16_f32 v120, v120, v97
	v_cvt_pk_bf16_f32 v121, v121, v97
	v_cvt_pk_bf16_f32 v122, v122, v97
	v_cvt_pk_bf16_f32 v123, v123, v97
	v_cvt_pk_bf16_f32 v124, v124, v97
	v_cvt_pk_bf16_f32 v125, v125, v97
	v_cvt_pk_bf16_f32 v126, v126, v97
	v_cvt_pk_bf16_f32 v127, v127, v97
	v_cvt_pk_bf16_f32 v128, v128, v97
	v_cvt_pk_bf16_f32 v129, v129, v97
	v_cvt_pk_bf16_f32 v130, v130, v97
	v_cvt_pk_bf16_f32 v131, v131, v97
	v_cvt_pk_bf16_f32 v132, v132, v97
	v_cvt_pk_bf16_f32 v133, v133, v97
	v_cvt_pk_bf16_f32 v134, v134, v97
	v_cvt_pk_bf16_f32 v135, v135, v97
	v_cvt_pk_bf16_f32 v136, v136, v97
	v_cvt_pk_bf16_f32 v137, v137, v97
	v_cvt_pk_bf16_f32 v138, v138, v97
	v_cvt_pk_bf16_f32 v139, v139, v97
	v_cvt_pk_bf16_f32 v140, v140, v97
	v_cvt_pk_bf16_f32 v141, v141, v97
	v_cvt_pk_bf16_f32 v142, v142, v97
	v_cvt_pk_bf16_f32 v143, v143, v97
	v_cvt_pk_bf16_f32 v144, v144, v97
	v_cvt_pk_bf16_f32 v145, v145, v97
	v_cvt_pk_bf16_f32 v146, v146, v97
	v_cvt_pk_bf16_f32 v147, v147, v97
	v_cvt_pk_bf16_f32 v148, v148, v97
	v_cvt_pk_bf16_f32 v149, v149, v97
	v_cvt_pk_bf16_f32 v150, v150, v97
	v_cvt_pk_bf16_f32 v151, v151, v97
	global_store_short v[30:31], v84, off
	global_store_short v[30:31], v85, off offset:64
	global_store_short v[30:31], v86, off offset:128
	global_store_short v[30:31], v87, off offset:192
	global_store_short v[30:31], v88, off offset:2048
	global_store_short v[30:31], v89, off offset:2112
	global_store_short v[30:31], v90, off offset:2176
	global_store_short v[30:31], v91, off offset:2240
	global_store_short v[66:67], v92, off
	global_store_short v[66:67], v93, off offset:64
	global_store_short v[66:67], v94, off offset:128
	global_store_short v[66:67], v95, off offset:192
	global_store_short v[66:67], v100, off offset:2048
	global_store_short v[66:67], v101, off offset:2112
	global_store_short v[66:67], v102, off offset:2176
	global_store_short v[66:67], v103, off offset:2240
	global_store_short v[70:71], v104, off
	global_store_short v[70:71], v105, off offset:64
	global_store_short v[70:71], v106, off offset:128
	global_store_short v[70:71], v107, off offset:192
	global_store_short v[70:71], v108, off offset:2048
	global_store_short v[70:71], v109, off offset:2112
	global_store_short v[70:71], v110, off offset:2176
	global_store_short v[70:71], v111, off offset:2240
	global_store_short v[74:75], v112, off
	global_store_short v[74:75], v113, off offset:64
	global_store_short v[74:75], v114, off offset:128
	global_store_short v[74:75], v115, off offset:192
	global_store_short v[74:75], v116, off offset:2048
	global_store_short v[74:75], v117, off offset:2112
	global_store_short v[74:75], v118, off offset:2176
	global_store_short v[74:75], v119, off offset:2240
	global_store_short v[2:3], v120, off
	global_store_short v[2:3], v121, off offset:64
	global_store_short v[2:3], v122, off offset:128
	global_store_short v[2:3], v123, off offset:192
	global_store_short v[2:3], v124, off offset:2048
	global_store_short v[2:3], v125, off offset:2112
	global_store_short v[2:3], v126, off offset:2176
	global_store_short v[2:3], v127, off offset:2240
	global_store_short v[18:19], v128, off
	global_store_short v[18:19], v129, off offset:64
	global_store_short v[18:19], v130, off offset:128
	global_store_short v[18:19], v131, off offset:192
	global_store_short v[18:19], v132, off offset:2048
	global_store_short v[18:19], v133, off offset:2112
	global_store_short v[18:19], v134, off offset:2176
	global_store_short v[18:19], v135, off offset:2240
	global_store_short v[34:35], v136, off
	global_store_short v[34:35], v137, off offset:64
	global_store_short v[34:35], v138, off offset:128
	global_store_short v[34:35], v139, off offset:192
	global_store_short v[34:35], v140, off offset:2048
	global_store_short v[34:35], v141, off offset:2112
	global_store_short v[34:35], v142, off offset:2176
	global_store_short v[34:35], v143, off offset:2240
	global_store_short v[50:51], v144, off
	global_store_short v[50:51], v145, off offset:64
	global_store_short v[50:51], v146, off offset:128
	global_store_short v[50:51], v147, off offset:192
	global_store_short v[50:51], v148, off offset:2048
	global_store_short v[50:51], v149, off offset:2112
	global_store_short v[50:51], v150, off offset:2176
	global_store_short v[50:51], v151, off offset:2240
	s_cbranch_execnz .LBB0_169
	s_branch .LBB0_192
